# v36 + next-tile LDS-DMA issued inside the QK MFMA pairs (instead of MLA unroll) + NA DMA scalarised + in-proj loop re-cut to 8 intervals
# baseline (speedup 1.0000x reference)
.LBB0_514:
	s_lshl_b32 s33, s18, 14
	v_add3_u32 v224, s33, v156, v155
	v_add3_u32 v225, s33, v157, v155
	ds_read_b128 v[170:173], v224 offset:40960
	ds_read_b128 v[174:177], v225 offset:40960
	ds_read_b128 v[178:181], v225 offset:32768
	ds_read_b128 v[182:185], v224 offset:32768
	s_andn2_b64 vcc, exec, s[4:5]
	s_add_i32 s31, s19, 1
	s_cbranch_vccnz .LBB0_516
	s_lshl_b32 s5, s18, 13
	s_xor_b32 s101, s5, 0x2000
	s_add_i32 s101, s30, s101
	s_add_i32 s5, s5, 0x10000
	s_lshl_b32 s33, s18, 14
	s_mov_b32 s4, s33
	s_xor_b32 s100, s33, 0x4000
	s_add_i32 s100, s29, s100
	s_add_i32 m0, s100, 0x8000
	s_sub_u32 s35, s19, 63
	s_cmp_lt_u32 s19, 63
	s_cselect_b32 vcc_lo, s31, s35
	s_cselect_b32 s19, s17, s26
	s_cselect_b32 s18, s16, s25
	s_cselect_b32 s35, s24, s28
	s_cselect_b32 s34, s23, s27
	s_mul_i32 vcc_hi, vcc_lo, 0x30000
	s_add_u32 s18, s18, vcc_hi
	s_addc_u32 s19, s19, 0
	s_lshl_b32 vcc_hi, vcc_lo, 18
	s_add_u32 s34, s34, vcc_hi
	s_addc_u32 s35, s35, 0
	global_load_lds_dwordx4 v208, s[18:19]
	s_mov_b32 m0, s100
	s_waitcnt lgkmcnt(2)
	v_mfma_f32_32x32x16_bf16 v[68:83], v[170:173], v[100:103], 0
	v_mfma_f32_32x32x16_bf16 v[68:83], v[174:177], v[104:107], v[68:83]
	v_add3_u32 v2, s4, v158, v155
	v_add3_u32 v145, s4, v160, v155
	ds_read_b128 v[170:173], v2 offset:32768
	ds_read_b128 v[174:177], v145 offset:32768
	global_load_lds_dwordx4 v209, s[34:35]
	s_add_i32 m0, s100, 0xa000
	s_waitcnt lgkmcnt(2)
	v_mfma_f32_32x32x16_bf16 v[84:99], v[178:181], v[104:107], 0
	v_mfma_f32_32x32x16_bf16 v[84:99], v[182:185], v[100:103], v[84:99]
	ds_read_b128 v[178:181], v145 offset:40960
	ds_read_b128 v[182:185], v2 offset:40960
	global_load_lds_dwordx4 v210, s[18:19]
	s_add_i32 m0, s100, 0x2000
	s_waitcnt lgkmcnt(2)
	v_mfma_f32_32x32x16_bf16 v[84:99], v[170:173], v[108:111], v[84:99]
	v_mfma_f32_32x32x16_bf16 v[84:99], v[174:177], v[112:115], v[84:99]
	v_add3_u32 v2, s4, v161, v155
	v_add3_u32 v145, s4, v162, v155
	ds_read_b128 v[170:173], v2 offset:40960
	ds_read_b128 v[174:177], v145 offset:40960
	global_load_lds_dwordx4 v211, s[34:35]
	s_mov_b32 m0, s101
	s_waitcnt lgkmcnt(2)
	v_mfma_f32_32x32x16_bf16 v[68:83], v[178:181], v[112:115], v[68:83]
	v_mfma_f32_32x32x16_bf16 v[68:83], v[182:185], v[108:111], v[68:83]
	ds_read_b128 v[178:181], v145 offset:32768
	ds_read_b128 v[182:185], v2 offset:32768
	global_load_lds_dwordx4 v212, s[18:19]
	s_waitcnt lgkmcnt(2)
	v_mfma_f32_32x32x16_bf16 v[68:83], v[170:173], v[116:119], v[68:83]
	v_mfma_f32_32x32x16_bf16 v[68:83], v[174:177], v[120:123], v[68:83]
	v_add3_u32 v2, s4, v163, v155
	v_add3_u32 v145, s4, v164, v155
	ds_read_b128 v[170:173], v2 offset:32768
	ds_read_b128 v[174:177], v145 offset:32768
	s_waitcnt lgkmcnt(2)
	v_mfma_f32_32x32x16_bf16 v[84:99], v[178:181], v[120:123], v[84:99]
	v_mfma_f32_32x32x16_bf16 v[84:99], v[182:185], v[116:119], v[84:99]
	ds_read_b128 v[178:181], v145 offset:40960
	ds_read_b128 v[182:185], v2 offset:40960
	s_waitcnt lgkmcnt(2)
	v_mfma_f32_32x32x16_bf16 v[84:99], v[170:173], v[124:127], v[84:99]
	v_mfma_f32_32x32x16_bf16 v[84:99], v[174:177], v[128:131], v[84:99]
	v_add3_u32 v2, s5, v156, v165
	v_add3_u32 v145, s5, v157, v165
	ds_read_b128 v[170:173], v2 offset:4096
	ds_read_b128 v[174:177], v145 offset:4096
	s_waitcnt lgkmcnt(2)
	v_mfma_f32_32x32x16_bf16 v[68:83], v[178:181], v[128:131], v[68:83]
	v_mfma_f32_32x32x16_bf16 v[68:83], v[182:185], v[124:127], v[68:83]
	ds_read_b128 v[178:181], v145
	ds_read_b128 v[182:185], v2
	s_waitcnt lgkmcnt(2)
	v_mfma_f32_32x32x16_bf16 v[68:83], v[170:173], v[186:189], v[68:83]
	v_mfma_f32_32x32x16_bf16 v[68:83], v[174:177], v[190:193], v[68:83]
	v_add3_u32 v2, s5, v158, v165
	v_add3_u32 v145, s5, v160, v165
	ds_read_b128 v[170:173], v2
	ds_read_b128 v[174:177], v145
	s_waitcnt lgkmcnt(2)
	v_mfma_f32_32x32x16_bf16 v[84:99], v[178:181], v[190:193], v[84:99]
	v_mfma_f32_32x32x16_bf16 v[84:99], v[182:185], v[186:189], v[84:99]
	ds_read_b128 v[178:181], v145 offset:4096
	ds_read_b128 v[182:185], v2 offset:4096
	s_waitcnt lgkmcnt(2)
	v_mfma_f32_32x32x16_bf16 v[84:99], v[170:173], v[194:197], v[84:99]
	v_mfma_f32_32x32x16_bf16 v[84:99], v[174:177], v[204:207], v[84:99]
	s_mov_b32 s4, 0x42ddb3d8
	s_waitcnt lgkmcnt(0)
	v_mfma_f32_32x32x16_bf16 v[68:83], v[178:181], v[204:207], v[68:83]
	v_mfma_f32_32x32x16_bf16 v[68:83], v[182:185], v[194:197], v[68:83]
	s_branch .Lmla_sm
.LBB0_516:
	s_add_i32 s4, s33, 0
	s_add_i32 s5, s34, 0
	s_add_i32 s5, s5, 0x10000
	s_waitcnt lgkmcnt(2)
	v_mfma_f32_32x32x16_bf16 v[68:83], v[170:173], v[100:103], 0
	v_mfma_f32_32x32x16_bf16 v[68:83], v[174:177], v[104:107], v[68:83]
	v_add3_u32 v2, s4, v158, v155
	v_add3_u32 v145, s4, v160, v155
	ds_read_b128 v[170:173], v2 offset:32768
	ds_read_b128 v[174:177], v145 offset:32768
	s_waitcnt lgkmcnt(2)
	v_mfma_f32_32x32x16_bf16 v[84:99], v[178:181], v[104:107], 0
	v_mfma_f32_32x32x16_bf16 v[84:99], v[182:185], v[100:103], v[84:99]
	ds_read_b128 v[178:181], v145 offset:40960
	ds_read_b128 v[182:185], v2 offset:40960
	s_waitcnt lgkmcnt(2)
	v_mfma_f32_32x32x16_bf16 v[84:99], v[170:173], v[108:111], v[84:99]
	v_mfma_f32_32x32x16_bf16 v[84:99], v[174:177], v[112:115], v[84:99]
	v_add3_u32 v2, s4, v161, v155
	v_add3_u32 v145, s4, v162, v155
	ds_read_b128 v[170:173], v2 offset:40960
	ds_read_b128 v[174:177], v145 offset:40960
	s_waitcnt lgkmcnt(2)
	v_mfma_f32_32x32x16_bf16 v[68:83], v[178:181], v[112:115], v[68:83]
	v_mfma_f32_32x32x16_bf16 v[68:83], v[182:185], v[108:111], v[68:83]
	ds_read_b128 v[178:181], v145 offset:32768
	ds_read_b128 v[182:185], v2 offset:32768
	s_waitcnt lgkmcnt(2)
	v_mfma_f32_32x32x16_bf16 v[68:83], v[170:173], v[116:119], v[68:83]
	v_mfma_f32_32x32x16_bf16 v[68:83], v[174:177], v[120:123], v[68:83]
	v_add3_u32 v2, s4, v163, v155
	v_add3_u32 v145, s4, v164, v155
	ds_read_b128 v[170:173], v2 offset:32768
	ds_read_b128 v[174:177], v145 offset:32768
	s_waitcnt lgkmcnt(2)
	v_mfma_f32_32x32x16_bf16 v[84:99], v[178:181], v[120:123], v[84:99]
	v_mfma_f32_32x32x16_bf16 v[84:99], v[182:185], v[116:119], v[84:99]
	ds_read_b128 v[178:181], v145 offset:40960
	ds_read_b128 v[182:185], v2 offset:40960
	s_waitcnt lgkmcnt(2)
	v_mfma_f32_32x32x16_bf16 v[84:99], v[170:173], v[124:127], v[84:99]
	v_mfma_f32_32x32x16_bf16 v[84:99], v[174:177], v[128:131], v[84:99]
	v_add3_u32 v2, s5, v156, v165
	v_add3_u32 v145, s5, v157, v165
	ds_read_b128 v[170:173], v2 offset:4096
	ds_read_b128 v[174:177], v145 offset:4096
	s_waitcnt lgkmcnt(2)
	v_mfma_f32_32x32x16_bf16 v[68:83], v[178:181], v[128:131], v[68:83]
	v_mfma_f32_32x32x16_bf16 v[68:83], v[182:185], v[124:127], v[68:83]
	ds_read_b128 v[178:181], v145
	ds_read_b128 v[182:185], v2
	s_waitcnt lgkmcnt(2)
	v_mfma_f32_32x32x16_bf16 v[68:83], v[170:173], v[186:189], v[68:83]
	v_mfma_f32_32x32x16_bf16 v[68:83], v[174:177], v[190:193], v[68:83]
	v_add3_u32 v2, s5, v158, v165
	v_add3_u32 v145, s5, v160, v165
	ds_read_b128 v[170:173], v2
	ds_read_b128 v[174:177], v145
	s_waitcnt lgkmcnt(2)
	v_mfma_f32_32x32x16_bf16 v[84:99], v[178:181], v[190:193], v[84:99]
	v_mfma_f32_32x32x16_bf16 v[84:99], v[182:185], v[186:189], v[84:99]
	ds_read_b128 v[178:181], v145 offset:4096
	ds_read_b128 v[182:185], v2 offset:4096
	s_waitcnt lgkmcnt(2)
	v_mfma_f32_32x32x16_bf16 v[84:99], v[170:173], v[194:197], v[84:99]
	v_mfma_f32_32x32x16_bf16 v[84:99], v[174:177], v[204:207], v[84:99]
	s_mov_b32 s4, 0x42ddb3d8
	s_waitcnt lgkmcnt(0)
	v_mfma_f32_32x32x16_bf16 v[68:83], v[178:181], v[204:207], v[68:83]
	v_mfma_f32_32x32x16_bf16 v[68:83], v[182:185], v[194:197], v[68:83]
.Lmla_sm:
	s_nop 10
	v_max_f32_e32 v2, v84, v85
	v_max3_f32 v2, v2, v86, v87
	v_max3_f32 v2, v2, v88, v89
	v_max3_f32 v2, v2, v90, v91
	v_max3_f32 v2, v2, v92, v93
	v_max3_f32 v2, v2, v94, v95
	v_max3_f32 v2, v2, v96, v97
	v_max3_f32 v2, v2, v98, v99
	v_max3_f32 v2, v2, v68, v69
	v_max3_f32 v2, v2, v70, v71
	v_max3_f32 v2, v2, v72, v73
	v_max3_f32 v2, v2, v74, v75
	v_max3_f32 v2, v2, v76, v77
	v_max3_f32 v2, v2, v78, v79
	v_max3_f32 v2, v2, v80, v81
	v_max3_f32 v2, v2, v82, v83
	v_mov_b32_e32 v145, v2
	s_nop 1
	v_permlane32_swap_b32_e32 v2, v145
	v_max_f32_e32 v2, v2, v145
	v_sub_f32_e32 v145, v2, v167
	v_cmp_ge_f32_e32 vcc, s4, v145
	s_cmp_eq_u64 vcc, exec
	s_cbranch_scc0 .Lmla_resc_slow
	v_mov_b32_e32 v2, 1.0
	s_mov_b64 s[4:5], -1
